# prep schedule: long ssm-coefficient items get their own blocks, orphaned items to blocks 136-159, transposes block index rotated by 96
# speedup vs baseline: 1.0006x; 1.0006x over previous
; __global__ void __launch_bounds__(512, 2) k_mega(P p) {
;     ...
;   const CP* pk = (const CP*)__builtin_amdgcn_kernarg_segment_ptr();
;   {
;     asm volatile("" : "+s"(pk));
;     for (int it = N_TR_ITEMS + blockIdx.x; it < N_PREP; it += gridDim.x) prep_item(*pk, it, smem);
;     prep_transposes(*pk, smem);
.LBB0_5:
	s_or_b64 exec, exec, s[4:5]
	s_add_i32 s3, s2, 0xb50
	s_mov_b32 s98, 0
	s_cmpk_lg_i32 s34, 0x100
	s_cbranch_scc1 .Lpi_init_done
	s_sub_i32 s4, s2, 0x80
	s_cmp_lt_u32 s4, 8
	s_cbranch_scc0 .Lpi_init_done
	s_add_i32 s3, s2, 0xc50
	s_mov_b32 s98, 1
.Lpi_init_done:
	s_cmpk_gt_i32 s3, 0xed7
	s_cbranch_scc1 .LBB0_56
	s_mov_b32 s22, 0
	s_mov_b32 s24, 0
	s_mov_b32 s26, 0
	s_mov_b32 s36, 0x54442d18
	s_mov_b32 s42, 0x6dc9c883
	s_mov_b32 s44, 0x33145c00
	s_mov_b32 s46, 0x252049c0
	s_mov_b32 s48, 0x9037ab78
	s_mov_b32 s50, 0x46cc5e42
	s_mov_b32 s52, 0xa17f65f6
	s_mov_b32 s54, 0x19f4ec90
	s_mov_b32 s56, 0x16c16967
	s_mov_b32 s58, 0x55555555
	s_mov_b32 s60, 0xb42fdfa7
	s_mov_b32 s62, 0xf9a43bb8
	s_mov_b32 s64, 0x796cde01
	s_mov_b32 s66, 0x19e83e5c
	s_mov_b32 s68, 0x11110bb3
	s_mov_b32 s33, 0x3fb8aa3b
	s_mov_b32 s82, 0xc2ce8ed0
	s_mov_b32 s21, 0
	s_mov_b32 s84, 0x42b17218
	s_mov_b32 s23, 0x41d00000
	s_mov_b32 s25, 0x7b000000
	s_movk_i32 s85, 0xff80
	s_mov_b32 s27, 0x7ff00000
	v_mov_b32_e32 v34, 0
	s_mov_b32 s31, 0x3ff921fb
	s_mov_b32 s37, 0xbff921fb
	s_mov_b32 s39, 0x3c91a626
	s_mov_b32 s40, 0x33145c07
	s_mov_b32 s43, 0x3fe45f30
	s_mov_b32 s45, 0xbc91a626
	s_mov_b32 s47, 0xb97b839a
	s_mov_b32 s49, 0x3e21eeb6
	s_mov_b32 s51, 0xbda907db
	s_mov_b32 s53, 0xbe927e4f
	s_mov_b32 s55, 0x3efa01a0
	s_mov_b32 s57, 0xbf56c16c
	s_mov_b32 s59, 0x3fa55555
	s_mov_b32 s61, 0xbe5ae600
	s_mov_b32 s63, 0x3de5e0b2
	s_mov_b32 s65, 0x3ec71de3
	s_mov_b32 s67, 0xbf2a01a0
	s_mov_b32 s69, 0x3f811111
	s_mov_b32 s71, 0xbfc55555
	s_brev_b32 s86, 1
	s_movk_i32 s87, 0x1f8
	s_movk_i32 s88, 0x800
	s_movk_i32 s89, 0x2410
	s_movk_i32 s90, 0x2000
	s_mov_b64 s[72:73], 0x20000
	s_movk_i32 s91, 0x1ff
	s_mov_b32 s92, 0xbfb8aa3b
	s_mov_b32 s93, 0x42ce8ed0
	s_mov_b32 s94, 0xc2b17218
	s_mov_b64 s[74:75], 0x800
	s_movk_i32 s95, 0x5ff
	s_movk_i32 s96, 0x6000
	s_mov_b64 s[76:77], 0xba000
	s_movk_i32 s97, 0x80
	s_mov_b64 s[78:79], 0xc0000
	v_mov_b32_e32 v1, 0x7f800000
	v_mov_b32_e32 v45, 0x40100000
	v_mov_b32_e32 v66, 0x3ff00000
	v_mov_b32_e32 v67, 0x7ff80000
	v_mov_b32_e32 v68, 0x1800000
	s_branch .LBB0_9

; __global__ void __launch_bounds__(512, 2) k_mega(P p) {
;     ...
;     for (int it = N_TR_ITEMS + blockIdx.x; it < N_PREP; it += gridDim.x) prep_item(*pk, it, smem);
.LBB0_8:
	s_cmpk_lg_i32 s34, 0x100
	s_cbranch_scc1 .Lpi_orig
	s_cmp_eq_u32 s98, 1
	s_cbranch_scc1 .LBB0_56
	s_addk_i32 s3, 0x100
	s_cmpk_gt_i32 s3, 0xed7
	s_cbranch_scc0 .LBB0_9
	s_mov_b32 s98, 1
	s_sub_i32 s4, s2, 0x88
	s_cmp_lt_u32 s4, 24
	s_cbranch_scc0 .LBB0_56
	s_add_i32 s3, s2, 0xb48
	s_cmp_lt_u32 s4, 8
	s_cbranch_scc1 .LBB0_9
	s_add_i32 s3, s2, 0xd40
	s_cmp_lt_u32 s4, 16
	s_cbranch_scc1 .LBB0_9
	s_add_i32 s3, s2, 0xe38
	s_branch .LBB0_9

; DI int get_tid() { int t = __builtin_amdgcn_workitem_id_x(); asm volatile("" : "+v"(t)); return t; }
; DI void prep_transposes(const CP& p, char* smem) {
;   const int tid = get_tid();
;   float* sm = (float*)smem;
;   int it = blockIdx.x;
;   if (it >= N_TR_ITEMS) return;
; __global__ void __launch_bounds__(512, 2) k_mega(P p) {
;     ...
;     for (int it = N_TR_ITEMS + blockIdx.x; it < N_PREP; it += gridDim.x) prep_item(*pk, it, smem);
;     prep_transposes(*pk, smem);
.LBB0_56:
	s_mov_b32 s98, s2
	s_cmpk_lg_i32 s34, 0x100
	s_cbranch_scc1 .Lpt_noremap
	s_addk_i32 s2, 0x60
	s_and_b32 s2, s2, 0xff

; __global__ void __launch_bounds__(512, 2) k_mega(P p) {
;     ...
;     for (int it = N_TR_ITEMS + blockIdx.x; it < N_PREP; it += gridDim.x) prep_item(*pk, it, smem);
;     prep_transposes(*pk, smem);
;     grid.sync();
.LBB0_180:
	s_mov_b32 s2, s98
	v_lshrrev_b32_e32 v1, 20, v0
	v_lshrrev_b32_e32 v0, 10, v0
	v_or_b32_e32 v0, v0, v1
	s_movk_i32 s3, 0x3ff
	v_and_or_b32 v0, v0, s3, v202
	v_cmp_eq_u32_e32 vcc, 0, v0
	s_barrier
	s_and_saveexec_b64 s[4:5], vcc
	s_cbranch_execz .LBB0_190
	buffer_wbl2 sc1
	s_waitcnt vmcnt(0)
	s_load_dwordx2 s[6:7], s[28:29], 0x58
	v_mov_b32_e32 v2, 0
	s_mov_b64 s[10:11], exec
	v_mbcnt_lo_u32_b32 v1, s10, 0
	v_mbcnt_hi_u32_b32 v1, s11, v1
	s_waitcnt lgkmcnt(0)
	global_load_dword v0, v2, s[6:7] offset:40
	v_cmp_eq_u32_e32 vcc, 0, v1
	s_and_saveexec_b64 s[12:13], vcc
	s_cbranch_execz .LBB0_183
	s_bcnt1_i32_b64 s3, s[10:11]
	v_mov_b32_e32 v3, s3
	global_atomic_add v3, v2, v3, s[6:7] offset:32 sc0
